# device-wide barrier: each workgroup invalidates its caches when it arrives (after its own last load) instead of after the release, and waits on the cross-XCD release word directly (one hop less)
# speedup vs baseline: 1.0170x; 1.0170x over previous
; __device__ __forceinline__ unsigned xb_ld(unsigned* p)              { return __hip_atomic_load(p, __ATOMIC_RELAXED, __HIP_MEMORY_SCOPE_AGENT); }
; __device__ __forceinline__ unsigned xb_add(unsigned* p, unsigned v) { return __hip_atomic_fetch_add(p, v, __ATOMIC_RELAXED, __HIP_MEMORY_SCOPE_AGENT); }
; #define XB_SPIN(cond, bar) do { unsigned _sp = 0; while (cond) { __builtin_amdgcn_s_sleep(1); \
;     if ((++_sp & 255u) == 0u) { if (xb_ld(&(bar)[XB_TMO])) break; if (_sp > XB_SPIN_CAP) { atomicAdd(&(bar)[XB_TMO], 1u); break; } } } } while (0)
; __device__ __forceinline__ void xcd_barrier(const XcdBarrier& b) {
;     asm volatile("s_waitcnt vmcnt(0)" ::: "memory");
;     __syncthreads();
;     if (threadIdx.x == 0) {
;         unsigned* bar = b.bar;
;         __builtin_amdgcn_s_waitcnt(0);
;         unsigned nloc = b.st[0], nx = b.st[1];
;         if (nloc == 0u) { xcd_barrier_complete(bar, b.x, nloc, nx); b.st[0] = nloc; b.st[1] = nx; }
;         const unsigned old = xb_add(&bar[XB_XSUB(b.x)], 1u);
;         const unsigned gen = old / nloc;
;         if (old + 1u == (gen + 1u) * nloc) {
;             __builtin_amdgcn_fence(__ATOMIC_RELEASE, "agent");
;             asm volatile("s_waitcnt vmcnt(0)" ::: "memory");
;             const unsigned og = xb_add(&bar[XB_TOP], 1u);
;             const unsigned tg = og / nx;
;             if (og + 1u == (tg + 1u) * nx) xb_add(&bar[XB_TOPGEN], 1u);
;             else XB_SPIN(xb_ld(&bar[XB_TOPGEN]) == tg, bar);
;             __builtin_amdgcn_fence(__ATOMIC_ACQUIRE, "agent");
;             xb_add(&bar[XB_XGEN(b.x)], 1u);
;             asm volatile("s_waitcnt vmcnt(0)" ::: "memory");
;         } else {
;             XB_SPIN(xb_ld(&bar[XB_XGEN(b.x)]) == gen, bar);
;             __builtin_amdgcn_fence(__ATOMIC_ACQUIRE, "agent");
;             asm volatile("s_waitcnt vmcnt(0)" ::: "memory");
;         }
.LBB0_90:
	s_mov_b64 s[6:7], exec
	v_readlane_b32 s4, v253, 36
	s_lshl_b32 s4, s4, 8
	v_readlane_b32 s8, v253, 34
	v_mbcnt_lo_u32_b32 v1, s6, 0
	v_readlane_b32 s9, v253, 35
	s_add_u32 s4, s8, s4
	v_mbcnt_hi_u32_b32 v1, s7, v1
	s_addc_u32 s5, s9, 0
	v_cmp_eq_u32_e32 vcc, 0, v1
	s_and_saveexec_b64 s[8:9], vcc
	s_cbranch_execz .LBB0_92
	s_bcnt1_i32_b64 s6, s[6:7]
	v_mov_b32_e32 v3, 0x1000
	v_mov_b32_e32 v4, s6
	global_atomic_add v3, v3, v4, s[4:5] offset:1024 sc0
	buffer_inv sc1
.LBB0_92:
	s_or_b64 exec, exec, s[8:9]
	v_cvt_f32_u32_e32 v4, v2
	s_waitcnt vmcnt(0)
	v_readfirstlane_b32 s6, v3
	v_sub_u32_e32 v3, 0, v2
	v_rcp_iflag_f32_e32 v4, v4
	v_add_u32_e32 v5, s6, v1
	v_mul_f32_e32 v4, 0x4f7ffffe, v4
	v_cvt_u32_f32_e32 v4, v4
	v_mul_lo_u32 v1, v3, v4
	v_mul_hi_u32 v1, v4, v1
	v_add_u32_e32 v1, v4, v1
	v_mul_hi_u32 v1, v5, v1
	v_mul_lo_u32 v3, v1, v2
	v_sub_u32_e32 v3, v5, v3
	v_add_u32_e32 v4, 1, v1
	v_cmp_ge_u32_e32 vcc, v3, v2
	s_nop 1
	v_cndmask_b32_e32 v1, v1, v4, vcc
	v_sub_u32_e32 v4, v3, v2
	v_cndmask_b32_e32 v3, v3, v4, vcc
	v_add_u32_e32 v4, 1, v1
	v_cmp_ge_u32_e32 vcc, v3, v2
	v_add_u32_e32 v3, 1, v5
	s_nop 0
	v_cndmask_b32_e32 v1, v1, v4, vcc
	v_mul_lo_u32 v4, v2, v1
	v_add_u32_e32 v2, v4, v2
	v_cmp_ne_u32_e32 vcc, v3, v2
	s_and_saveexec_b64 s[6:7], vcc
	s_xor_b64 s[6:7], exec, s[6:7]
	s_cbranch_execz .LBB0_106
	s_waitcnt lgkmcnt(0)
	s_add_u32 s12, s16, 0x1e03500
	s_addc_u32 s13, s17, 0
	v_mov_b32_e32 v0, 0
	global_load_dword v0, v0, s[12:13] sc1
	s_waitcnt vmcnt(0)
	v_cmp_eq_u32_e32 vcc, v0, v1
	s_and_saveexec_b64 s[8:9], vcc
	s_cbranch_execz .LBB0_105
	s_add_u32 s10, s16, 0x1e00200
	s_addc_u32 s11, s17, 0
	s_mov_b32 s26, 1
	s_mov_b64 s[14:15], 0
	v_mov_b32_e32 v0, 0
	s_branch .LBB0_96

; __device__ __forceinline__ unsigned xb_ld(unsigned* p)              { return __hip_atomic_load(p, __ATOMIC_RELAXED, __HIP_MEMORY_SCOPE_AGENT); }
; #define XB_SPIN(cond, bar) do { unsigned _sp = 0; while (cond) { __builtin_amdgcn_s_sleep(1); \
;     if ((++_sp & 255u) == 0u) { if (xb_ld(&(bar)[XB_TMO])) break; if (_sp > XB_SPIN_CAP) { atomicAdd(&(bar)[XB_TMO], 1u); break; } } } } while (0)
; __device__ __forceinline__ void xcd_barrier(const XcdBarrier& b) {
;     ...
;             XB_SPIN(xb_ld(&bar[XB_XGEN(b.x)]) == gen, bar);
;             __builtin_amdgcn_fence(__ATOMIC_ACQUIRE, "agent");
;             asm volatile("s_waitcnt vmcnt(0)" ::: "memory");
;         }
.LBB0_105:
	s_or_b64 exec, exec, s[8:9]
	s_waitcnt vmcnt(0)
	s_waitcnt vmcnt(0)

; __device__ __forceinline__ unsigned xb_add(unsigned* p, unsigned v) { return __hip_atomic_fetch_add(p, v, __ATOMIC_RELAXED, __HIP_MEMORY_SCOPE_AGENT); }
; __device__ __forceinline__ void xcd_barrier(const XcdBarrier& b) {
;     ...
;             __builtin_amdgcn_fence(__ATOMIC_ACQUIRE, "agent");
;             xb_add(&bar[XB_XGEN(b.x)], 1u);
;             asm volatile("s_waitcnt vmcnt(0)" ::: "memory");
.LBB0_123:
	s_or_b64 exec, exec, s[6:7]
	s_mov_b64 s[6:7], exec
	v_mbcnt_lo_u32_b32 v0, s6, 0
	v_mbcnt_hi_u32_b32 v0, s7, v0
	v_cmp_eq_u32_e32 vcc, 0, v0
	s_waitcnt vmcnt(0)
	s_and_saveexec_b64 s[8:9], vcc
	s_cbranch_execz .LBB0_125
	s_bcnt1_i32_b64 s6, s[6:7]
	v_mov_b32_e32 v0, 0x2000
	v_mov_b32_e32 v1, s6
	global_atomic_add v0, v1, s[4:5] offset:1024
.LBB0_125:
	s_or_b64 exec, exec, s[8:9]
	s_waitcnt vmcnt(0)

; __device__ __forceinline__ unsigned xb_add(unsigned* p, unsigned v) { return __hip_atomic_fetch_add(p, v, __ATOMIC_RELAXED, __HIP_MEMORY_SCOPE_AGENT); }
; __device__ __forceinline__ void xcd_barrier(const XcdBarrier& b) {
;     ...
;             __builtin_amdgcn_fence(__ATOMIC_ACQUIRE, "agent");
;             xb_add(&bar[XB_XGEN(b.x)], 1u);
;             asm volatile("s_waitcnt vmcnt(0)" ::: "memory");
.LBB0_246:
	s_or_b64 exec, exec, s[6:7]
	s_mov_b64 s[6:7], exec
	v_mbcnt_lo_u32_b32 v0, s6, 0
	v_mbcnt_hi_u32_b32 v0, s7, v0
	v_cmp_eq_u32_e32 vcc, 0, v0
	s_waitcnt vmcnt(0)
	s_and_saveexec_b64 s[8:9], vcc
	s_cbranch_execz .LBB0_248
	s_bcnt1_i32_b64 s6, s[6:7]
	v_mov_b32_e32 v0, 0x2000
	v_mov_b32_e32 v1, s6
	global_atomic_add v0, v1, s[4:5] offset:1024
.LBB0_248:
	s_or_b64 exec, exec, s[8:9]
	s_waitcnt vmcnt(0)

; __device__ __forceinline__ unsigned xb_ld(unsigned* p)              { return __hip_atomic_load(p, __ATOMIC_RELAXED, __HIP_MEMORY_SCOPE_AGENT); }
; __device__ __forceinline__ unsigned xb_add(unsigned* p, unsigned v) { return __hip_atomic_fetch_add(p, v, __ATOMIC_RELAXED, __HIP_MEMORY_SCOPE_AGENT); }
; #define XB_SPIN(cond, bar) do { unsigned _sp = 0; while (cond) { __builtin_amdgcn_s_sleep(1); \
;     if ((++_sp & 255u) == 0u) { if (xb_ld(&(bar)[XB_TMO])) break; if (_sp > XB_SPIN_CAP) { atomicAdd(&(bar)[XB_TMO], 1u); break; } } } } while (0)
; __device__ __forceinline__ void xcd_barrier(const XcdBarrier& b) {
;     ...
;         const unsigned old = xb_add(&bar[XB_XSUB(b.x)], 1u);
;         const unsigned gen = old / nloc;
;         if (old + 1u == (gen + 1u) * nloc) {
;             __builtin_amdgcn_fence(__ATOMIC_RELEASE, "agent");
;             asm volatile("s_waitcnt vmcnt(0)" ::: "memory");
;             const unsigned og = xb_add(&bar[XB_TOP], 1u);
;             const unsigned tg = og / nx;
;             if (og + 1u == (tg + 1u) * nx) xb_add(&bar[XB_TOPGEN], 1u);
;             else XB_SPIN(xb_ld(&bar[XB_TOPGEN]) == tg, bar);
;             __builtin_amdgcn_fence(__ATOMIC_ACQUIRE, "agent");
;             xb_add(&bar[XB_XGEN(b.x)], 1u);
;             asm volatile("s_waitcnt vmcnt(0)" ::: "memory");
;         } else {
;             XB_SPIN(xb_ld(&bar[XB_XGEN(b.x)]) == gen, bar);
;             __builtin_amdgcn_fence(__ATOMIC_ACQUIRE, "agent");
;             asm volatile("s_waitcnt vmcnt(0)" ::: "memory");
;         }
.LBB0_319:
	s_or_b64 exec, exec, s[8:9]
	v_cvt_f32_u32_e32 v4, v2
	s_waitcnt vmcnt(0)
	v_readfirstlane_b32 s6, v3
	v_sub_u32_e32 v3, 0, v2
	v_rcp_iflag_f32_e32 v4, v4
	v_add_u32_e32 v5, s6, v1
	v_mul_f32_e32 v4, 0x4f7ffffe, v4
	v_cvt_u32_f32_e32 v4, v4
	v_mul_lo_u32 v1, v3, v4
	v_mul_hi_u32 v1, v4, v1
	v_add_u32_e32 v1, v4, v1
	v_mul_hi_u32 v1, v5, v1
	v_mul_lo_u32 v3, v1, v2
	v_sub_u32_e32 v3, v5, v3
	v_add_u32_e32 v4, 1, v1
	v_cmp_ge_u32_e32 vcc, v3, v2
	s_nop 1
	v_cndmask_b32_e32 v1, v1, v4, vcc
	v_sub_u32_e32 v4, v3, v2
	v_cndmask_b32_e32 v3, v3, v4, vcc
	v_add_u32_e32 v4, 1, v1
	v_cmp_ge_u32_e32 vcc, v3, v2
	v_add_u32_e32 v3, 1, v5
	s_nop 0
	v_cndmask_b32_e32 v1, v1, v4, vcc
	v_mul_lo_u32 v4, v2, v1
	v_add_u32_e32 v2, v4, v2
	v_cmp_ne_u32_e32 vcc, v3, v2
	s_and_saveexec_b64 s[6:7], vcc
	s_xor_b64 s[6:7], exec, s[6:7]
	s_cbranch_execz .LBB0_333
	s_waitcnt lgkmcnt(0)
	s_add_u32 s14, s16, 0x1e03500
	s_addc_u32 s15, s17, 0
	v_mov_b32_e32 v0, 0
	global_load_dword v0, v0, s[14:15] sc1
	s_waitcnt vmcnt(0)
	v_cmp_eq_u32_e32 vcc, v0, v1
	s_and_saveexec_b64 s[8:9], vcc
	s_cbranch_execz .LBB0_332
	s_add_u32 s12, s16, 0x1e00200
	s_addc_u32 s13, s17, 0
	s_mov_b32 s28, 1
	s_mov_b64 s[18:19], 0
	v_mov_b32_e32 v0, 0
	s_branch .LBB0_323

; __device__ __forceinline__ unsigned xb_add(unsigned* p, unsigned v) { return __hip_atomic_fetch_add(p, v, __ATOMIC_RELAXED, __HIP_MEMORY_SCOPE_AGENT); }
; __device__ __forceinline__ void xcd_barrier(const XcdBarrier& b) {
;     ...
;             __builtin_amdgcn_fence(__ATOMIC_ACQUIRE, "agent");
;             xb_add(&bar[XB_XGEN(b.x)], 1u);
;             asm volatile("s_waitcnt vmcnt(0)" ::: "memory");
.LBB0_350:
	s_or_b64 exec, exec, s[6:7]
	s_mov_b64 s[6:7], exec
	v_mbcnt_lo_u32_b32 v0, s6, 0
	v_mbcnt_hi_u32_b32 v0, s7, v0
	v_cmp_eq_u32_e32 vcc, 0, v0
	s_waitcnt vmcnt(0)
	s_and_saveexec_b64 s[8:9], vcc
	s_cbranch_execz .LBB0_352
	s_bcnt1_i32_b64 s6, s[6:7]
	v_mov_b32_e32 v0, 0x2000
	v_mov_b32_e32 v1, s6
	global_atomic_add v0, v1, s[4:5] offset:1024
.LBB0_352:
	s_or_b64 exec, exec, s[8:9]
	s_waitcnt vmcnt(0)

; __device__ __forceinline__ unsigned xb_ld(unsigned* p)              { return __hip_atomic_load(p, __ATOMIC_RELAXED, __HIP_MEMORY_SCOPE_AGENT); }
; __device__ __forceinline__ unsigned xb_add(unsigned* p, unsigned v) { return __hip_atomic_fetch_add(p, v, __ATOMIC_RELAXED, __HIP_MEMORY_SCOPE_AGENT); }
; #define XB_SPIN(cond, bar) do { unsigned _sp = 0; while (cond) { __builtin_amdgcn_s_sleep(1); \
;     if ((++_sp & 255u) == 0u) { if (xb_ld(&(bar)[XB_TMO])) break; if (_sp > XB_SPIN_CAP) { atomicAdd(&(bar)[XB_TMO], 1u); break; } } } } while (0)
; __device__ __forceinline__ void xcd_barrier(const XcdBarrier& b) {
;     asm volatile("s_waitcnt vmcnt(0)" ::: "memory");
;     __syncthreads();
;     if (threadIdx.x == 0) {
;         unsigned* bar = b.bar;
;         __builtin_amdgcn_s_waitcnt(0);
;         unsigned nloc = b.st[0], nx = b.st[1];
;         if (nloc == 0u) { xcd_barrier_complete(bar, b.x, nloc, nx); b.st[0] = nloc; b.st[1] = nx; }
;         const unsigned old = xb_add(&bar[XB_XSUB(b.x)], 1u);
;         const unsigned gen = old / nloc;
;         if (old + 1u == (gen + 1u) * nloc) {
;             __builtin_amdgcn_fence(__ATOMIC_RELEASE, "agent");
;             asm volatile("s_waitcnt vmcnt(0)" ::: "memory");
;             const unsigned og = xb_add(&bar[XB_TOP], 1u);
;             const unsigned tg = og / nx;
;             if (og + 1u == (tg + 1u) * nx) xb_add(&bar[XB_TOPGEN], 1u);
;             else XB_SPIN(xb_ld(&bar[XB_TOPGEN]) == tg, bar);
;             __builtin_amdgcn_fence(__ATOMIC_ACQUIRE, "agent");
;             xb_add(&bar[XB_XGEN(b.x)], 1u);
;             asm volatile("s_waitcnt vmcnt(0)" ::: "memory");
;         } else {
;             XB_SPIN(xb_ld(&bar[XB_XGEN(b.x)]) == gen, bar);
;             __builtin_amdgcn_fence(__ATOMIC_ACQUIRE, "agent");
;             asm volatile("s_waitcnt vmcnt(0)" ::: "memory");
;         }
.LBB0_547:
	s_mov_b64 s[8:9], exec
	v_readlane_b32 s4, v253, 36
	s_lshl_b32 s4, s4, 8
	v_readlane_b32 s12, v253, 34
	v_mbcnt_lo_u32_b32 v1, s8, 0
	v_readlane_b32 s13, v253, 35
	s_add_u32 s4, s12, s4
	v_mbcnt_hi_u32_b32 v1, s9, v1
	s_addc_u32 s5, s13, 0
	v_cmp_eq_u32_e32 vcc, 0, v1
	s_and_saveexec_b64 s[12:13], vcc
	s_cbranch_execz .LBB0_549
	s_bcnt1_i32_b64 s8, s[8:9]
	v_mov_b32_e32 v3, 0x1000
	v_mov_b32_e32 v4, s8
	global_atomic_add v3, v3, v4, s[4:5] offset:1024 sc0
	buffer_inv sc1
.LBB0_549:
	s_or_b64 exec, exec, s[12:13]
	v_cvt_f32_u32_e32 v4, v2
	s_waitcnt vmcnt(0)
	v_readfirstlane_b32 s8, v3
	v_sub_u32_e32 v3, 0, v2
	v_rcp_iflag_f32_e32 v4, v4
	v_add_u32_e32 v5, s8, v1
	v_mul_f32_e32 v4, 0x4f7ffffe, v4
	v_cvt_u32_f32_e32 v4, v4
	v_mul_lo_u32 v1, v3, v4
	v_mul_hi_u32 v1, v4, v1
	v_add_u32_e32 v1, v4, v1
	v_mul_hi_u32 v1, v5, v1
	v_mul_lo_u32 v3, v1, v2
	v_sub_u32_e32 v3, v5, v3
	v_add_u32_e32 v4, 1, v1
	v_cmp_ge_u32_e32 vcc, v3, v2
	s_nop 1
	v_cndmask_b32_e32 v1, v1, v4, vcc
	v_sub_u32_e32 v4, v3, v2
	v_cndmask_b32_e32 v3, v3, v4, vcc
	v_add_u32_e32 v4, 1, v1
	v_cmp_ge_u32_e32 vcc, v3, v2
	v_add_u32_e32 v3, 1, v5
	s_nop 0
	v_cndmask_b32_e32 v1, v1, v4, vcc
	v_mul_lo_u32 v4, v2, v1
	v_add_u32_e32 v2, v4, v2
	v_cmp_ne_u32_e32 vcc, v3, v2
	s_and_saveexec_b64 s[8:9], vcc
	s_xor_b64 s[8:9], exec, s[8:9]
	s_cbranch_execz .LBB0_563
	s_waitcnt lgkmcnt(0)
	s_add_u32 s22, s16, 0x1e03500
	s_addc_u32 s23, s17, 0
	v_mov_b32_e32 v0, 0
	global_load_dword v0, v0, s[22:23] sc1
	s_waitcnt vmcnt(0)
	v_cmp_eq_u32_e32 vcc, v0, v1
	s_and_saveexec_b64 s[12:13], vcc
	s_cbranch_execz .LBB0_562
	s_add_u32 s20, s16, 0x1e00200
	s_addc_u32 s21, s17, 0
	s_mov_b32 s33, 1
	s_mov_b64 s[24:25], 0
	v_mov_b32_e32 v0, 0
	s_branch .LBB0_553

; __device__ __forceinline__ unsigned xb_ld(unsigned* p)              { return __hip_atomic_load(p, __ATOMIC_RELAXED, __HIP_MEMORY_SCOPE_AGENT); }
; #define XB_SPIN(cond, bar) do { unsigned _sp = 0; while (cond) { __builtin_amdgcn_s_sleep(1); \
;     if ((++_sp & 255u) == 0u) { if (xb_ld(&(bar)[XB_TMO])) break; if (_sp > XB_SPIN_CAP) { atomicAdd(&(bar)[XB_TMO], 1u); break; } } } } while (0)
; __device__ __forceinline__ void xcd_barrier(const XcdBarrier& b) {
;     ...
;             XB_SPIN(xb_ld(&bar[XB_XGEN(b.x)]) == gen, bar);
;             __builtin_amdgcn_fence(__ATOMIC_ACQUIRE, "agent");
;             asm volatile("s_waitcnt vmcnt(0)" ::: "memory");
;         }
.LBB0_562:
	s_or_b64 exec, exec, s[12:13]
	s_waitcnt vmcnt(0)
	s_waitcnt vmcnt(0)

; __device__ __forceinline__ unsigned xb_add(unsigned* p, unsigned v) { return __hip_atomic_fetch_add(p, v, __ATOMIC_RELAXED, __HIP_MEMORY_SCOPE_AGENT); }
; __device__ __forceinline__ void xcd_barrier(const XcdBarrier& b) {
;     ...
;             __builtin_amdgcn_fence(__ATOMIC_ACQUIRE, "agent");
;             xb_add(&bar[XB_XGEN(b.x)], 1u);
;             asm volatile("s_waitcnt vmcnt(0)" ::: "memory");
.LBB0_580:
	s_or_b64 exec, exec, s[8:9]
	s_mov_b64 s[8:9], exec
	v_mbcnt_lo_u32_b32 v0, s8, 0
	v_mbcnt_hi_u32_b32 v0, s9, v0
	v_cmp_eq_u32_e32 vcc, 0, v0
	s_waitcnt vmcnt(0)
	s_and_saveexec_b64 s[12:13], vcc
	s_cbranch_execz .LBB0_582
	s_bcnt1_i32_b64 s8, s[8:9]
	v_mov_b32_e32 v0, 0x2000
	v_mov_b32_e32 v1, s8
	global_atomic_add v0, v1, s[4:5] offset:1024
.LBB0_582:
	s_or_b64 exec, exec, s[12:13]
	s_waitcnt vmcnt(0)

; __device__ __forceinline__ unsigned xb_add(unsigned* p, unsigned v) { return __hip_atomic_fetch_add(p, v, __ATOMIC_RELAXED, __HIP_MEMORY_SCOPE_AGENT); }
; __device__ __forceinline__ void xcd_barrier(const XcdBarrier& b) {
;     ...
;             __builtin_amdgcn_fence(__ATOMIC_ACQUIRE, "agent");
;             xb_add(&bar[XB_XGEN(b.x)], 1u);
;             asm volatile("s_waitcnt vmcnt(0)" ::: "memory");
.LBB0_637:
	s_or_b64 exec, exec, s[8:9]
	s_mov_b64 s[8:9], exec
	v_mbcnt_lo_u32_b32 v0, s8, 0
	v_mbcnt_hi_u32_b32 v0, s9, v0
	v_cmp_eq_u32_e32 vcc, 0, v0
	s_waitcnt vmcnt(0)
	s_and_saveexec_b64 s[12:13], vcc
	s_cbranch_execz .LBB0_639
	s_bcnt1_i32_b64 s8, s[8:9]
	v_mov_b32_e32 v0, 0x2000
	v_mov_b32_e32 v1, s8
	global_atomic_add v0, v1, s[4:5] offset:1024
.LBB0_639:
	s_or_b64 exec, exec, s[12:13]
	s_waitcnt vmcnt(0)

; __device__ __forceinline__ unsigned xb_ld(unsigned* p)              { return __hip_atomic_load(p, __ATOMIC_RELAXED, __HIP_MEMORY_SCOPE_AGENT); }
; __device__ __forceinline__ unsigned xb_add(unsigned* p, unsigned v) { return __hip_atomic_fetch_add(p, v, __ATOMIC_RELAXED, __HIP_MEMORY_SCOPE_AGENT); }
; #define XB_SPIN(cond, bar) do { unsigned _sp = 0; while (cond) { __builtin_amdgcn_s_sleep(1); \
;     if ((++_sp & 255u) == 0u) { if (xb_ld(&(bar)[XB_TMO])) break; if (_sp > XB_SPIN_CAP) { atomicAdd(&(bar)[XB_TMO], 1u); break; } } } } while (0)
; __device__ __forceinline__ void xcd_barrier(const XcdBarrier& b) {
;     ...
;         const unsigned old = xb_add(&bar[XB_XSUB(b.x)], 1u);
;         const unsigned gen = old / nloc;
;         if (old + 1u == (gen + 1u) * nloc) {
;             __builtin_amdgcn_fence(__ATOMIC_RELEASE, "agent");
;             asm volatile("s_waitcnt vmcnt(0)" ::: "memory");
;             const unsigned og = xb_add(&bar[XB_TOP], 1u);
;             const unsigned tg = og / nx;
;             if (og + 1u == (tg + 1u) * nx) xb_add(&bar[XB_TOPGEN], 1u);
;             else XB_SPIN(xb_ld(&bar[XB_TOPGEN]) == tg, bar);
;             __builtin_amdgcn_fence(__ATOMIC_ACQUIRE, "agent");
;             xb_add(&bar[XB_XGEN(b.x)], 1u);
;             asm volatile("s_waitcnt vmcnt(0)" ::: "memory");
;         } else {
;             XB_SPIN(xb_ld(&bar[XB_XGEN(b.x)]) == gen, bar);
;             __builtin_amdgcn_fence(__ATOMIC_ACQUIRE, "agent");
;             asm volatile("s_waitcnt vmcnt(0)" ::: "memory");
;         }
.LBB0_701:
	s_or_b64 exec, exec, s[8:9]
	v_cvt_f32_u32_e32 v4, v2
	s_waitcnt vmcnt(0)
	v_readfirstlane_b32 s6, v3
	v_sub_u32_e32 v3, 0, v2
	v_rcp_iflag_f32_e32 v4, v4
	v_add_u32_e32 v5, s6, v1
	v_mul_f32_e32 v4, 0x4f7ffffe, v4
	v_cvt_u32_f32_e32 v4, v4
	v_mul_lo_u32 v1, v3, v4
	v_mul_hi_u32 v1, v4, v1
	v_add_u32_e32 v1, v4, v1
	v_mul_hi_u32 v1, v5, v1
	v_mul_lo_u32 v3, v1, v2
	v_sub_u32_e32 v3, v5, v3
	v_add_u32_e32 v4, 1, v1
	v_cmp_ge_u32_e32 vcc, v3, v2
	s_nop 1
	v_cndmask_b32_e32 v1, v1, v4, vcc
	v_sub_u32_e32 v4, v3, v2
	v_cndmask_b32_e32 v3, v3, v4, vcc
	v_add_u32_e32 v4, 1, v1
	v_cmp_ge_u32_e32 vcc, v3, v2
	v_add_u32_e32 v3, 1, v5
	s_nop 0
	v_cndmask_b32_e32 v1, v1, v4, vcc
	v_mul_lo_u32 v4, v2, v1
	v_add_u32_e32 v2, v4, v2
	v_cmp_ne_u32_e32 vcc, v3, v2
	s_and_saveexec_b64 s[6:7], vcc
	s_xor_b64 s[6:7], exec, s[6:7]
	s_cbranch_execz .LBB0_715
	s_waitcnt lgkmcnt(0)
	s_add_u32 s12, s16, 0x1e03500
	s_addc_u32 s13, s17, 0
	v_mov_b32_e32 v0, 0
	global_load_dword v0, v0, s[12:13] sc1
	s_waitcnt vmcnt(0)
	v_cmp_eq_u32_e32 vcc, v0, v1
	s_and_saveexec_b64 s[8:9], vcc
	s_cbranch_execz .LBB0_714
	s_add_u32 s10, s16, 0x1e00200
	s_addc_u32 s11, s17, 0
	s_mov_b32 s33, 1
	s_mov_b64 s[22:23], 0
	v_mov_b32_e32 v0, 0
	s_branch .LBB0_705

; __device__ __forceinline__ unsigned xb_add(unsigned* p, unsigned v) { return __hip_atomic_fetch_add(p, v, __ATOMIC_RELAXED, __HIP_MEMORY_SCOPE_AGENT); }
; __device__ __forceinline__ void xcd_barrier(const XcdBarrier& b) {
;     ...
;             __builtin_amdgcn_fence(__ATOMIC_ACQUIRE, "agent");
;             xb_add(&bar[XB_XGEN(b.x)], 1u);
;             asm volatile("s_waitcnt vmcnt(0)" ::: "memory");
.LBB0_732:
	s_or_b64 exec, exec, s[6:7]
	s_mov_b64 s[6:7], exec
	v_mbcnt_lo_u32_b32 v0, s6, 0
	v_mbcnt_hi_u32_b32 v0, s7, v0
	v_cmp_eq_u32_e32 vcc, 0, v0
	s_waitcnt vmcnt(0)
	s_and_saveexec_b64 s[8:9], vcc
	s_cbranch_execz .LBB0_734
	s_bcnt1_i32_b64 s6, s[6:7]
	v_mov_b32_e32 v0, 0x2000
	v_mov_b32_e32 v1, s6
	global_atomic_add v0, v1, s[4:5] offset:1024
.LBB0_734:
	s_or_b64 exec, exec, s[8:9]
	s_waitcnt vmcnt(0)

; __device__ __forceinline__ unsigned xb_ld(unsigned* p)              { return __hip_atomic_load(p, __ATOMIC_RELAXED, __HIP_MEMORY_SCOPE_AGENT); }
; __device__ __forceinline__ unsigned xb_add(unsigned* p, unsigned v) { return __hip_atomic_fetch_add(p, v, __ATOMIC_RELAXED, __HIP_MEMORY_SCOPE_AGENT); }
; #define XB_SPIN(cond, bar) do { unsigned _sp = 0; while (cond) { __builtin_amdgcn_s_sleep(1); \
;     if ((++_sp & 255u) == 0u) { if (xb_ld(&(bar)[XB_TMO])) break; if (_sp > XB_SPIN_CAP) { atomicAdd(&(bar)[XB_TMO], 1u); break; } } } } while (0)
; __device__ __forceinline__ void xcd_barrier(const XcdBarrier& b) {
;     ...
;         const unsigned old = xb_add(&bar[XB_XSUB(b.x)], 1u);
;         const unsigned gen = old / nloc;
;         if (old + 1u == (gen + 1u) * nloc) {
;             __builtin_amdgcn_fence(__ATOMIC_RELEASE, "agent");
;             asm volatile("s_waitcnt vmcnt(0)" ::: "memory");
;             const unsigned og = xb_add(&bar[XB_TOP], 1u);
;             const unsigned tg = og / nx;
;             if (og + 1u == (tg + 1u) * nx) xb_add(&bar[XB_TOPGEN], 1u);
;             else XB_SPIN(xb_ld(&bar[XB_TOPGEN]) == tg, bar);
;             __builtin_amdgcn_fence(__ATOMIC_ACQUIRE, "agent");
;             xb_add(&bar[XB_XGEN(b.x)], 1u);
;             asm volatile("s_waitcnt vmcnt(0)" ::: "memory");
;         } else {
;             XB_SPIN(xb_ld(&bar[XB_XGEN(b.x)]) == gen, bar);
;             __builtin_amdgcn_fence(__ATOMIC_ACQUIRE, "agent");
;             asm volatile("s_waitcnt vmcnt(0)" ::: "memory");
;         }
.LBB0_782:
	s_or_b64 exec, exec, s[8:9]
	v_cvt_f32_u32_e32 v4, v2
	s_waitcnt vmcnt(0)
	v_readfirstlane_b32 s6, v3
	v_sub_u32_e32 v3, 0, v2
	v_rcp_iflag_f32_e32 v4, v4
	v_add_u32_e32 v5, s6, v1
	v_mul_f32_e32 v4, 0x4f7ffffe, v4
	v_cvt_u32_f32_e32 v4, v4
	v_mul_lo_u32 v1, v3, v4
	v_mul_hi_u32 v1, v4, v1
	v_add_u32_e32 v1, v4, v1
	v_mul_hi_u32 v1, v5, v1
	v_mul_lo_u32 v3, v1, v2
	v_sub_u32_e32 v3, v5, v3
	v_add_u32_e32 v4, 1, v1
	v_cmp_ge_u32_e32 vcc, v3, v2
	s_nop 1
	v_cndmask_b32_e32 v1, v1, v4, vcc
	v_sub_u32_e32 v4, v3, v2
	v_cndmask_b32_e32 v3, v3, v4, vcc
	v_add_u32_e32 v4, 1, v1
	v_cmp_ge_u32_e32 vcc, v3, v2
	v_add_u32_e32 v3, 1, v5
	s_nop 0
	v_cndmask_b32_e32 v1, v1, v4, vcc
	v_mul_lo_u32 v4, v2, v1
	v_add_u32_e32 v2, v4, v2
	v_cmp_ne_u32_e32 vcc, v3, v2
	s_and_saveexec_b64 s[6:7], vcc
	s_xor_b64 s[6:7], exec, s[6:7]
	s_cbranch_execz .LBB0_796
	s_waitcnt lgkmcnt(0)
	s_add_u32 s12, s16, 0x1e03500
	s_addc_u32 s13, s17, 0
	v_mov_b32_e32 v0, 0
	global_load_dword v0, v0, s[12:13] sc1
	s_waitcnt vmcnt(0)
	v_cmp_eq_u32_e32 vcc, v0, v1
	s_and_saveexec_b64 s[8:9], vcc
	s_cbranch_execz .LBB0_795
	s_add_u32 s10, s16, 0x1e00200
	s_addc_u32 s11, s17, 0
	s_mov_b32 s33, 1
	s_mov_b64 s[18:19], 0
	v_mov_b32_e32 v0, 0
	s_branch .LBB0_786

; __device__ __forceinline__ unsigned xb_add(unsigned* p, unsigned v) { return __hip_atomic_fetch_add(p, v, __ATOMIC_RELAXED, __HIP_MEMORY_SCOPE_AGENT); }
; __device__ __forceinline__ void xcd_barrier(const XcdBarrier& b) {
;     ...
;             __builtin_amdgcn_fence(__ATOMIC_ACQUIRE, "agent");
;             xb_add(&bar[XB_XGEN(b.x)], 1u);
;             asm volatile("s_waitcnt vmcnt(0)" ::: "memory");
.LBB0_813:
	s_or_b64 exec, exec, s[6:7]
	s_mov_b64 s[6:7], exec
	v_mbcnt_lo_u32_b32 v0, s6, 0
	v_mbcnt_hi_u32_b32 v0, s7, v0
	v_cmp_eq_u32_e32 vcc, 0, v0
	s_waitcnt vmcnt(0)
	s_and_saveexec_b64 s[8:9], vcc
	s_cbranch_execz .LBB0_815
	s_bcnt1_i32_b64 s6, s[6:7]
	v_mov_b32_e32 v0, 0x2000
	v_mov_b32_e32 v1, s6
	global_atomic_add v0, v1, s[4:5] offset:1024
.LBB0_815:
	s_or_b64 exec, exec, s[8:9]
	s_waitcnt vmcnt(0)

; __device__ __forceinline__ unsigned xb_add(unsigned* p, unsigned v) { return __hip_atomic_fetch_add(p, v, __ATOMIC_RELAXED, __HIP_MEMORY_SCOPE_AGENT); }
; __device__ __forceinline__ void xcd_barrier(const XcdBarrier& b) {
;     ...
;             __builtin_amdgcn_fence(__ATOMIC_ACQUIRE, "agent");
;             xb_add(&bar[XB_XGEN(b.x)], 1u);
;             asm volatile("s_waitcnt vmcnt(0)" ::: "memory");
.LBB0_886:
	s_or_b64 exec, exec, s[6:7]
	s_mov_b64 s[6:7], exec
	v_mbcnt_lo_u32_b32 v0, s6, 0
	v_mbcnt_hi_u32_b32 v0, s7, v0
	v_cmp_eq_u32_e32 vcc, 0, v0
	s_waitcnt vmcnt(0)
	s_and_saveexec_b64 s[8:9], vcc
	s_cbranch_execz .LBB0_888
	s_bcnt1_i32_b64 s6, s[6:7]
	v_mov_b32_e32 v0, 0x2000
	v_mov_b32_e32 v1, s6
	global_atomic_add v0, v1, s[4:5] offset:1024
.LBB0_888:
	s_or_b64 exec, exec, s[8:9]
	s_waitcnt vmcnt(0)

; __device__ __forceinline__ unsigned xb_ld(unsigned* p)              { return __hip_atomic_load(p, __ATOMIC_RELAXED, __HIP_MEMORY_SCOPE_AGENT); }
; __device__ __forceinline__ unsigned xb_add(unsigned* p, unsigned v) { return __hip_atomic_fetch_add(p, v, __ATOMIC_RELAXED, __HIP_MEMORY_SCOPE_AGENT); }
; #define XB_SPIN(cond, bar) do { unsigned _sp = 0; while (cond) { __builtin_amdgcn_s_sleep(1); \
;     if ((++_sp & 255u) == 0u) { if (xb_ld(&(bar)[XB_TMO])) break; if (_sp > XB_SPIN_CAP) { atomicAdd(&(bar)[XB_TMO], 1u); break; } } } } while (0)
; __device__ __forceinline__ void xcd_barrier(const XcdBarrier& b) {
;     asm volatile("s_waitcnt vmcnt(0)" ::: "memory");
;     __syncthreads();
;     if (threadIdx.x == 0) {
;         unsigned* bar = b.bar;
;         __builtin_amdgcn_s_waitcnt(0);
;         unsigned nloc = b.st[0], nx = b.st[1];
;         if (nloc == 0u) { xcd_barrier_complete(bar, b.x, nloc, nx); b.st[0] = nloc; b.st[1] = nx; }
;         const unsigned old = xb_add(&bar[XB_XSUB(b.x)], 1u);
;         const unsigned gen = old / nloc;
;         if (old + 1u == (gen + 1u) * nloc) {
;             __builtin_amdgcn_fence(__ATOMIC_RELEASE, "agent");
;             asm volatile("s_waitcnt vmcnt(0)" ::: "memory");
;             const unsigned og = xb_add(&bar[XB_TOP], 1u);
;             const unsigned tg = og / nx;
;             if (og + 1u == (tg + 1u) * nx) xb_add(&bar[XB_TOPGEN], 1u);
;             else XB_SPIN(xb_ld(&bar[XB_TOPGEN]) == tg, bar);
;             __builtin_amdgcn_fence(__ATOMIC_ACQUIRE, "agent");
;             xb_add(&bar[XB_XGEN(b.x)], 1u);
;             asm volatile("s_waitcnt vmcnt(0)" ::: "memory");
;         } else {
;             XB_SPIN(xb_ld(&bar[XB_XGEN(b.x)]) == gen, bar);
;             __builtin_amdgcn_fence(__ATOMIC_ACQUIRE, "agent");
;             asm volatile("s_waitcnt vmcnt(0)" ::: "memory");
;         }
.LBB0_952:
	s_mov_b64 s[4:5], exec
	v_readlane_b32 s2, v253, 36
	s_lshl_b32 s2, s2, 8
	v_readlane_b32 s6, v253, 34
	v_mbcnt_lo_u32_b32 v1, s4, 0
	v_readlane_b32 s7, v253, 35
	s_add_u32 s2, s6, s2
	v_mbcnt_hi_u32_b32 v1, s5, v1
	s_addc_u32 s3, s7, 0
	v_cmp_eq_u32_e32 vcc, 0, v1
	s_and_saveexec_b64 s[6:7], vcc
	s_cbranch_execz .LBB0_954
	s_bcnt1_i32_b64 s4, s[4:5]
	v_mov_b32_e32 v3, 0x1000
	v_mov_b32_e32 v4, s4
	global_atomic_add v3, v3, v4, s[2:3] offset:1024 sc0
	buffer_inv sc1
.LBB0_954:
	s_or_b64 exec, exec, s[6:7]
	v_cvt_f32_u32_e32 v4, v2
	s_waitcnt vmcnt(0)
	v_readfirstlane_b32 s4, v3
	v_sub_u32_e32 v3, 0, v2
	v_rcp_iflag_f32_e32 v4, v4
	v_add_u32_e32 v5, s4, v1
	v_mul_f32_e32 v4, 0x4f7ffffe, v4
	v_cvt_u32_f32_e32 v4, v4
	v_mul_lo_u32 v1, v3, v4
	v_mul_hi_u32 v1, v4, v1
	v_add_u32_e32 v1, v4, v1
	v_mul_hi_u32 v1, v5, v1
	v_mul_lo_u32 v3, v1, v2
	v_sub_u32_e32 v3, v5, v3
	v_add_u32_e32 v4, 1, v1
	v_cmp_ge_u32_e32 vcc, v3, v2
	s_nop 1
	v_cndmask_b32_e32 v1, v1, v4, vcc
	v_sub_u32_e32 v4, v3, v2
	v_cndmask_b32_e32 v3, v3, v4, vcc
	v_add_u32_e32 v4, 1, v1
	v_cmp_ge_u32_e32 vcc, v3, v2
	v_add_u32_e32 v3, 1, v5
	s_nop 0
	v_cndmask_b32_e32 v1, v1, v4, vcc
	v_mul_lo_u32 v4, v2, v1
	v_add_u32_e32 v2, v4, v2
	v_cmp_ne_u32_e32 vcc, v3, v2
	s_and_saveexec_b64 s[4:5], vcc
	s_xor_b64 s[4:5], exec, s[4:5]
	s_cbranch_execz .LBB0_968
	s_waitcnt lgkmcnt(0)
	s_add_u32 s10, s16, 0x1e03500
	s_addc_u32 s11, s17, 0
	v_mov_b32_e32 v0, 0
	global_load_dword v0, v0, s[10:11] sc1
	s_waitcnt vmcnt(0)
	v_cmp_eq_u32_e32 vcc, v0, v1
	s_and_saveexec_b64 s[6:7], vcc
	s_cbranch_execz .LBB0_967
	s_add_u32 s8, s16, 0x1e00200
	s_addc_u32 s9, s17, 0
	s_mov_b32 s26, 1
	s_mov_b64 s[12:13], 0
	v_mov_b32_e32 v0, 0
	s_branch .LBB0_958

; __device__ __forceinline__ unsigned xb_ld(unsigned* p)              { return __hip_atomic_load(p, __ATOMIC_RELAXED, __HIP_MEMORY_SCOPE_AGENT); }
; #define XB_SPIN(cond, bar) do { unsigned _sp = 0; while (cond) { __builtin_amdgcn_s_sleep(1); \
;     if ((++_sp & 255u) == 0u) { if (xb_ld(&(bar)[XB_TMO])) break; if (_sp > XB_SPIN_CAP) { atomicAdd(&(bar)[XB_TMO], 1u); break; } } } } while (0)
; __device__ __forceinline__ void xcd_barrier(const XcdBarrier& b) {
;     ...
;             XB_SPIN(xb_ld(&bar[XB_XGEN(b.x)]) == gen, bar);
;             __builtin_amdgcn_fence(__ATOMIC_ACQUIRE, "agent");
;             asm volatile("s_waitcnt vmcnt(0)" ::: "memory");
;         }
.LBB0_967:
	s_or_b64 exec, exec, s[6:7]
	s_waitcnt vmcnt(0)
	s_waitcnt vmcnt(0)

; __device__ __forceinline__ unsigned xb_add(unsigned* p, unsigned v) { return __hip_atomic_fetch_add(p, v, __ATOMIC_RELAXED, __HIP_MEMORY_SCOPE_AGENT); }
; __device__ __forceinline__ void xcd_barrier(const XcdBarrier& b) {
;     ...
;             __builtin_amdgcn_fence(__ATOMIC_ACQUIRE, "agent");
;             xb_add(&bar[XB_XGEN(b.x)], 1u);
;             asm volatile("s_waitcnt vmcnt(0)" ::: "memory");
.LBB0_985:
	s_or_b64 exec, exec, s[4:5]
	s_mov_b64 s[4:5], exec
	v_mbcnt_lo_u32_b32 v0, s4, 0
	v_mbcnt_hi_u32_b32 v0, s5, v0
	v_cmp_eq_u32_e32 vcc, 0, v0
	s_waitcnt vmcnt(0)
	s_and_saveexec_b64 s[6:7], vcc
	s_cbranch_execz .LBB0_987
	s_bcnt1_i32_b64 s4, s[4:5]
	v_mov_b32_e32 v0, 0x2000
	v_mov_b32_e32 v1, s4
	global_atomic_add v0, v1, s[2:3] offset:1024
.LBB0_987:
	s_or_b64 exec, exec, s[6:7]
	s_waitcnt vmcnt(0)
